# v37: v30 + P0 modulation units: the bias load is issued before the LDS reduction loop instead of after it
# speedup vs baseline: 1.0026x; 1.0026x over previous
; DEV void mod_phase(LAS char* shm, const float* c, const float* w_mod, const float* b_mod, float* mod, unsigned* modcnt) {
;     ...
;     for (int it = blockIdx.x; it < 192; it += gridDim.x) {
;         const int l = it / 96, n0 = (it % 96) * 32, cq = tid & 7, kg = tid >> 3;
;         const float* W = w_mod + (size_t)l * DM * 3 * DM + n0 + 4 * cq;
;         float acc[BATCH][4];
; #pragma unroll
;         for (int b = 0; b < BATCH; ++b) { acc[b][0] = acc[b][1] = acc[b][2] = acc[b][3] = 0.f; }
;         float4 w[16];
; #pragma unroll
;         for (int k = 0; k < 16; ++k) w[k] = *(const float4*)(W + (size_t)(kg * 16 + k) * 3 * DM);
; #pragma unroll
;         for (int k = 0; k < 16; ++k) {
; #pragma unroll
;             for (int b = 0; b < BATCH; ++b) { const float s_ = sc[b * DM + kg * 16 + k]; acc[b][0] += s_ * w[k].x; acc[b][1] += s_ * w[k].y; acc[b][2] += s_ * w[k].z; acc[b][3] += s_ * w[k].w; }
.LBB0_11:
	s_mul_hi_i32 s6, s19, 0x2aaaaaab
	s_lshr_b32 s7, s6, 31
	s_ashr_i32 s6, s6, 4
	s_add_i32 s14, s6, s7
	s_mul_i32 s6, s14, 0x60
	s_sub_i32 s6, s19, s6
	s_lshl_b32 s6, s6, 5
	s_mul_i32 s15, s14, 0xc00000
	s_mul_hi_i32 s7, s14, 0xc00000
	s_add_u32 s15, s2, s15
	s_addc_u32 s20, s3, s7
	s_ashr_i32 s7, s6, 31
	s_lshl_b64 s[16:17], s[6:7], 2
	s_add_u32 s16, s15, s16
	s_addc_u32 s17, s20, s17
	v_lshl_add_u64 v[124:125], s[16:17], 0, v[86:87]
	v_lshl_add_u64 v[2:3], v[124:125], 0, v[92:93]
	global_load_dwordx4 v[34:37], v[2:3], off
	v_lshl_add_u64 v[2:3], v[124:125], 0, v[94:95]
	global_load_dwordx4 v[30:33], v[2:3], off
	v_lshl_add_u64 v[2:3], v[124:125], 0, v[96:97]
	global_load_dwordx4 v[66:69], v[2:3], off
	v_lshl_add_u64 v[2:3], v[124:125], 0, v[98:99]
	global_load_dwordx4 v[46:49], v[2:3], off
	v_lshl_add_u64 v[26:27], v[124:125], 0, v[100:101]
	ds_read_b128 v[70:73], v1
	ds_read_b128 v[38:41], v1 offset:16
	ds_read_b128 v[74:77], v1 offset:4096
	ds_read_b128 v[22:25], v1 offset:4112
	ds_read_b128 v[78:81], v1 offset:8192
	ds_read_b128 v[18:21], v1 offset:8208
	ds_read_b128 v[62:65], v1 offset:12288
	ds_read_b128 v[14:17], v1 offset:12304
	ds_read_b128 v[58:61], v1 offset:16384
	ds_read_b128 v[10:13], v1 offset:16400
	ds_read_b128 v[54:57], v1 offset:20480
	ds_read_b128 v[6:9], v1 offset:20496
	ds_read_b128 v[50:53], v1 offset:24576
	ds_read_b128 v[2:5], v1 offset:24592
	global_load_dwordx4 v[42:45], v[26:27], off
	v_lshl_add_u64 v[126:127], v[124:125], 0, v[102:103]
	v_lshl_add_u64 v[134:135], v[124:125], 0, v[104:105]
	v_lshl_add_u64 v[138:139], v[124:125], 0, v[106:107]
	ds_read_b128 v[82:85], v1 offset:28672
	ds_read_b128 v[26:29], v1 offset:28688
	global_load_dwordx4 v[130:133], v[126:127], off
	s_nop 0
	global_load_dwordx4 v[134:137], v[134:135], off
	s_nop 0
	global_load_dwordx4 v[138:141], v[138:139], off
	s_waitcnt vmcnt(7) lgkmcnt(14)
	v_pk_fma_f32 v[126:127], v[34:35], v[70:71], 0 op_sel_hi:[1,0,0]
	v_pk_fma_f32 v[142:143], v[36:37], v[70:71], 0 op_sel_hi:[1,0,0]
	s_waitcnt lgkmcnt(13)
	v_pk_fma_f32 v[144:145], v[34:35], v[74:75], 0 op_sel_hi:[1,0,0]
	v_pk_fma_f32 v[146:147], v[36:37], v[74:75], 0 op_sel_hi:[1,0,0]
	s_waitcnt lgkmcnt(9)
	v_pk_fma_f32 v[152:153], v[34:35], v[62:63], 0 op_sel_hi:[1,0,0]
	s_waitcnt lgkmcnt(3)
	v_pk_fma_f32 v[164:165], v[34:35], v[50:51], 0 op_sel_hi:[1,0,0]
	v_pk_fma_f32 v[166:167], v[36:37], v[50:51], 0 op_sel_hi:[1,0,0]
	v_pk_fma_f32 v[148:149], v[34:35], v[78:79], 0 op_sel_hi:[1,0,0]
	v_pk_fma_f32 v[150:151], v[36:37], v[78:79], 0 op_sel_hi:[1,0,0]
	v_pk_fma_f32 v[154:155], v[36:37], v[62:63], 0 op_sel_hi:[1,0,0]
	v_pk_fma_f32 v[156:157], v[34:35], v[58:59], 0 op_sel_hi:[1,0,0]
	v_pk_fma_f32 v[158:159], v[36:37], v[58:59], 0 op_sel_hi:[1,0,0]
	v_pk_fma_f32 v[160:161], v[34:35], v[54:55], 0 op_sel_hi:[1,0,0]
	v_pk_fma_f32 v[162:163], v[36:37], v[54:55], 0 op_sel_hi:[1,0,0]
	s_waitcnt lgkmcnt(1)
	v_pk_fma_f32 v[34:35], v[34:35], v[82:83], 0 op_sel_hi:[1,0,0]
	v_pk_fma_f32 v[36:37], v[36:37], v[82:83], 0 op_sel_hi:[1,0,0]
	s_waitcnt vmcnt(6)
	v_pk_fma_f32 v[126:127], v[30:31], v[70:71], v[126:127] op_sel:[0,1,0]
	v_pk_fma_f32 v[70:71], v[32:33], v[70:71], v[142:143] op_sel:[0,1,0]
	v_pk_fma_f32 v[142:143], v[30:31], v[74:75], v[144:145] op_sel:[0,1,0]
	v_pk_fma_f32 v[74:75], v[32:33], v[74:75], v[146:147] op_sel:[0,1,0]
	v_pk_fma_f32 v[146:147], v[30:31], v[62:63], v[152:153] op_sel:[0,1,0]
	v_pk_fma_f32 v[152:153], v[30:31], v[50:51], v[164:165] op_sel:[0,1,0]
	v_pk_fma_f32 v[50:51], v[32:33], v[50:51], v[166:167] op_sel:[0,1,0]
	v_pk_fma_f32 v[144:145], v[30:31], v[78:79], v[148:149] op_sel:[0,1,0]
	v_pk_fma_f32 v[78:79], v[32:33], v[78:79], v[150:151] op_sel:[0,1,0]
	v_pk_fma_f32 v[62:63], v[32:33], v[62:63], v[154:155] op_sel:[0,1,0]
	v_pk_fma_f32 v[148:149], v[30:31], v[58:59], v[156:157] op_sel:[0,1,0]
	v_pk_fma_f32 v[58:59], v[32:33], v[58:59], v[158:159] op_sel:[0,1,0]
	v_pk_fma_f32 v[150:151], v[30:31], v[54:55], v[160:161] op_sel:[0,1,0]
	v_pk_fma_f32 v[54:55], v[32:33], v[54:55], v[162:163] op_sel:[0,1,0]
	v_pk_fma_f32 v[30:31], v[30:31], v[82:83], v[34:35] op_sel:[0,1,0]
	v_pk_fma_f32 v[32:33], v[32:33], v[82:83], v[36:37] op_sel:[0,1,0]
	s_waitcnt vmcnt(5)
	v_pk_fma_f32 v[34:35], v[66:67], v[72:73], v[126:127] op_sel_hi:[1,0,1]
	v_pk_fma_f32 v[36:37], v[68:69], v[72:73], v[70:71] op_sel_hi:[1,0,1]
	v_pk_fma_f32 v[126:127], v[66:67], v[64:65], v[146:147] op_sel_hi:[1,0,1]
	v_pk_fma_f32 v[146:147], v[66:67], v[52:53], v[152:153] op_sel_hi:[1,0,1]
	v_pk_fma_f32 v[50:51], v[68:69], v[52:53], v[50:51] op_sel_hi:[1,0,1]
	v_mov_b32_e32 v52, v73
	v_pk_fma_f32 v[62:63], v[68:69], v[64:65], v[62:63] op_sel_hi:[1,0,1]
	s_waitcnt vmcnt(4)
; DEV void mod_phase(LAS char* shm, const float* c, const float* w_mod, const float* b_mod, float* mod, unsigned* modcnt) {
;     ...
;         for (int k = 0; k < 16; ++k) w[k] = *(const float4*)(W + (size_t)(kg * 16 + k) * 3 * DM);
; #pragma unroll
;         for (int k = 0; k < 16; ++k) {
; #pragma unroll
;             for (int b = 0; b < BATCH; ++b) { const float s_ = sc[b * DM + kg * 16 + k]; acc[b][0] += s_ * w[k].x; acc[b][1] += s_ * w[k].y; acc[b][2] += s_ * w[k].z; acc[b][3] += s_ * w[k].w; }
	v_pk_fma_f32 v[34:35], v[46:47], v[52:53], v[34:35] op_sel_hi:[1,0,1]
	v_pk_fma_f32 v[36:37], v[48:49], v[52:53], v[36:37] op_sel_hi:[1,0,1]
	v_mov_b32_e32 v52, v65
	v_pk_fma_f32 v[70:71], v[66:67], v[76:77], v[142:143] op_sel_hi:[1,0,1]
	v_pk_fma_f32 v[82:83], v[66:67], v[80:81], v[144:145] op_sel_hi:[1,0,1]
	v_pk_fma_f32 v[78:79], v[68:69], v[80:81], v[78:79] op_sel_hi:[1,0,1]
	v_pk_fma_f32 v[142:143], v[66:67], v[60:61], v[148:149] op_sel_hi:[1,0,1]
	v_pk_fma_f32 v[58:59], v[68:69], v[60:61], v[58:59] op_sel_hi:[1,0,1]
	v_pk_fma_f32 v[144:145], v[66:67], v[56:57], v[150:151] op_sel_hi:[1,0,1]
	v_pk_fma_f32 v[54:55], v[68:69], v[56:57], v[54:55] op_sel_hi:[1,0,1]
	v_mov_b32_e32 v56, v77
	v_mov_b32_e32 v60, v81
	v_pk_fma_f32 v[64:65], v[46:47], v[52:53], v[126:127] op_sel_hi:[1,0,1]
	v_pk_fma_f32 v[62:63], v[48:49], v[52:53], v[62:63] op_sel_hi:[1,0,1]
	v_mov_b32_e32 v52, v61
	v_pk_fma_f32 v[74:75], v[68:69], v[76:77], v[74:75] op_sel_hi:[1,0,1]
	v_pk_fma_f32 v[30:31], v[66:67], v[84:85], v[30:31] op_sel_hi:[1,0,1]
	v_pk_fma_f32 v[66:67], v[46:47], v[56:57], v[70:71] op_sel_hi:[1,0,1]
	v_pk_fma_f32 v[70:71], v[46:47], v[60:61], v[82:83] op_sel_hi:[1,0,1]
	v_pk_fma_f32 v[72:73], v[48:49], v[60:61], v[78:79] op_sel_hi:[1,0,1]
	v_pk_fma_f32 v[60:61], v[46:47], v[52:53], v[142:143] op_sel_hi:[1,0,1]
	v_pk_fma_f32 v[58:59], v[48:49], v[52:53], v[58:59] op_sel_hi:[1,0,1]
	v_mov_b32_e32 v52, v57
	v_pk_fma_f32 v[32:33], v[68:69], v[84:85], v[32:33] op_sel_hi:[1,0,1]
	v_pk_fma_f32 v[68:69], v[48:49], v[56:57], v[74:75] op_sel_hi:[1,0,1]
	v_pk_fma_f32 v[56:57], v[46:47], v[52:53], v[144:145] op_sel_hi:[1,0,1]
	v_pk_fma_f32 v[54:55], v[48:49], v[52:53], v[54:55] op_sel_hi:[1,0,1]
	v_mov_b32_e32 v52, v53
	v_pk_fma_f32 v[74:75], v[46:47], v[52:53], v[146:147] op_sel_hi:[1,0,1]
	v_pk_fma_f32 v[50:51], v[48:49], v[52:53], v[50:51] op_sel_hi:[1,0,1]
	v_mov_b32_e32 v52, v85
	v_pk_fma_f32 v[46:47], v[46:47], v[52:53], v[30:31] op_sel_hi:[1,0,1]
	v_lshl_add_u64 v[30:31], v[124:125], 0, v[108:109]
	v_pk_fma_f32 v[48:49], v[48:49], v[52:53], v[32:33] op_sel_hi:[1,0,1]
	global_load_dwordx4 v[30:33], v[30:31], off
	s_waitcnt vmcnt(4)
	v_pk_fma_f32 v[34:35], v[42:43], v[38:39], v[34:35] op_sel_hi:[1,0,1]
	v_pk_fma_f32 v[36:37], v[44:45], v[38:39], v[36:37] op_sel_hi:[1,0,1]
	v_pk_fma_f32 v[52:53], v[42:43], v[22:23], v[66:67] op_sel_hi:[1,0,1]
	v_pk_fma_f32 v[66:67], v[44:45], v[22:23], v[68:69] op_sel_hi:[1,0,1]
	v_pk_fma_f32 v[68:69], v[42:43], v[18:19], v[70:71] op_sel_hi:[1,0,1]
	v_pk_fma_f32 v[70:71], v[44:45], v[18:19], v[72:73] op_sel_hi:[1,0,1]
	v_pk_fma_f32 v[56:57], v[42:43], v[6:7], v[56:57] op_sel_hi:[1,0,1]
	v_pk_fma_f32 v[54:55], v[44:45], v[6:7], v[54:55] op_sel_hi:[1,0,1]
	v_pk_fma_f32 v[72:73], v[42:43], v[2:3], v[74:75] op_sel_hi:[1,0,1]
	v_pk_fma_f32 v[50:51], v[44:45], v[2:3], v[50:51] op_sel_hi:[1,0,1]
	v_pk_fma_f32 v[64:65], v[42:43], v[14:15], v[64:65] op_sel_hi:[1,0,1]
	v_pk_fma_f32 v[62:63], v[44:45], v[14:15], v[62:63] op_sel_hi:[1,0,1]
	v_pk_fma_f32 v[60:61], v[42:43], v[10:11], v[60:61] op_sel_hi:[1,0,1]
	v_pk_fma_f32 v[58:59], v[44:45], v[10:11], v[58:59] op_sel_hi:[1,0,1]
	s_waitcnt lgkmcnt(0)
	v_pk_fma_f32 v[42:43], v[42:43], v[26:27], v[46:47] op_sel_hi:[1,0,1]
	v_pk_fma_f32 v[44:45], v[44:45], v[26:27], v[48:49] op_sel_hi:[1,0,1]
	s_waitcnt vmcnt(3)
	v_pk_fma_f32 v[34:35], v[130:131], v[38:39], v[34:35] op_sel:[0,1,0]
	v_pk_fma_f32 v[36:37], v[132:133], v[38:39], v[36:37] op_sel:[0,1,0]
	v_pk_fma_f32 v[56:57], v[130:131], v[6:7], v[56:57] op_sel:[0,1,0]
	v_pk_fma_f32 v[6:7], v[132:133], v[6:7], v[54:55] op_sel:[0,1,0]
	v_pk_fma_f32 v[54:55], v[130:131], v[2:3], v[72:73] op_sel:[0,1,0]
	v_pk_fma_f32 v[2:3], v[132:133], v[2:3], v[50:51] op_sel:[0,1,0]
	v_pk_fma_f32 v[38:39], v[130:131], v[22:23], v[52:53] op_sel:[0,1,0]
	v_pk_fma_f32 v[22:23], v[132:133], v[22:23], v[66:67] op_sel:[0,1,0]
	v_pk_fma_f32 v[42:43], v[130:131], v[26:27], v[42:43] op_sel:[0,1,0]
	v_pk_fma_f32 v[26:27], v[132:133], v[26:27], v[44:45] op_sel:[0,1,0]
	s_waitcnt vmcnt(2)
	v_pk_fma_f32 v[44:45], v[134:135], v[40:41], v[34:35] op_sel_hi:[1,0,1]
	v_pk_fma_f32 v[50:51], v[136:137], v[40:41], v[36:37] op_sel_hi:[1,0,1]
	v_pk_fma_f32 v[54:55], v[134:135], v[4:5], v[54:55] op_sel_hi:[1,0,1]
	v_pk_fma_f32 v[2:3], v[136:137], v[4:5], v[2:3] op_sel_hi:[1,0,1]
	v_mov_b32_e32 v4, v41
	v_pk_fma_f32 v[46:47], v[130:131], v[18:19], v[68:69] op_sel:[0,1,0]
	v_pk_fma_f32 v[18:19], v[132:133], v[18:19], v[70:71] op_sel:[0,1,0]
	v_pk_fma_f32 v[52:53], v[130:131], v[10:11], v[60:61] op_sel:[0,1,0]
	v_pk_fma_f32 v[10:11], v[132:133], v[10:11], v[58:59] op_sel:[0,1,0]
	v_pk_fma_f32 v[58:59], v[134:135], v[24:25], v[38:39] op_sel_hi:[1,0,1]
	v_pk_fma_f32 v[22:23], v[136:137], v[24:25], v[22:23] op_sel_hi:[1,0,1]
	s_waitcnt vmcnt(1)
; DEV void mod_phase(LAS char* shm, const float* c, const float* w_mod, const float* b_mod, float* mod, unsigned* modcnt) {
;     ...
;         for (int k = 0; k < 16; ++k) w[k] = *(const float4*)(W + (size_t)(kg * 16 + k) * 3 * DM);
; #pragma unroll
;         for (int k = 0; k < 16; ++k) {
; #pragma unroll
;             for (int b = 0; b < BATCH; ++b) { const float s_ = sc[b * DM + kg * 16 + k]; acc[b][0] += s_ * w[k].x; acc[b][1] += s_ * w[k].y; acc[b][2] += s_ * w[k].z; acc[b][3] += s_ * w[k].w; }
	v_pk_fma_f32 v[44:45], v[138:139], v[4:5], v[44:45] op_sel_hi:[1,0,1]
	v_pk_fma_f32 v[50:51], v[140:141], v[4:5], v[50:51] op_sel_hi:[1,0,1]
	v_mov_b32_e32 v4, v25
	v_pk_fma_f32 v[48:49], v[130:131], v[14:15], v[64:65] op_sel:[0,1,0]
	v_pk_fma_f32 v[14:15], v[132:133], v[14:15], v[62:63] op_sel:[0,1,0]
	v_pk_fma_f32 v[46:47], v[134:135], v[20:21], v[46:47] op_sel_hi:[1,0,1]
	v_pk_fma_f32 v[18:19], v[136:137], v[20:21], v[18:19] op_sel_hi:[1,0,1]
	v_pk_fma_f32 v[58:59], v[138:139], v[4:5], v[58:59] op_sel_hi:[1,0,1]
	v_pk_fma_f32 v[60:61], v[140:141], v[4:5], v[22:23] op_sel_hi:[1,0,1]
	v_mov_b32_e32 v4, v21
	v_pk_fma_f32 v[48:49], v[134:135], v[16:17], v[48:49] op_sel_hi:[1,0,1]
	v_pk_fma_f32 v[14:15], v[136:137], v[16:17], v[14:15] op_sel_hi:[1,0,1]
	v_pk_fma_f32 v[46:47], v[138:139], v[4:5], v[46:47] op_sel_hi:[1,0,1]
	v_pk_fma_f32 v[62:63], v[140:141], v[4:5], v[18:19] op_sel_hi:[1,0,1]
	v_mov_b32_e32 v4, v17
	v_lshl_add_u64 v[34:35], v[124:125], 0, v[110:111]
	v_pk_fma_f32 v[52:53], v[134:135], v[12:13], v[52:53] op_sel_hi:[1,0,1]
	v_pk_fma_f32 v[10:11], v[136:137], v[12:13], v[10:11] op_sel_hi:[1,0,1]
	v_pk_fma_f32 v[64:65], v[138:139], v[4:5], v[48:49] op_sel_hi:[1,0,1]
	v_pk_fma_f32 v[70:71], v[140:141], v[4:5], v[14:15] op_sel_hi:[1,0,1]
	v_mov_b32_e32 v4, v13
	global_load_dwordx4 v[34:37], v[34:35], off
	v_pk_fma_f32 v[6:7], v[136:137], v[8:9], v[6:7] op_sel_hi:[1,0,1]
	v_lshl_add_u64 v[38:39], v[124:125], 0, v[112:113]
	v_pk_fma_f32 v[78:79], v[138:139], v[4:5], v[52:53] op_sel_hi:[1,0,1]
	v_pk_fma_f32 v[80:81], v[140:141], v[4:5], v[10:11] op_sel_hi:[1,0,1]
	v_mov_b32_e32 v4, v9
	global_load_dwordx4 v[38:41], v[38:39], off
	v_pk_fma_f32 v[130:131], v[140:141], v[4:5], v[6:7] op_sel_hi:[1,0,1]
	v_lshl_add_u64 v[6:7], v[124:125], 0, v[114:115]
	v_pk_fma_f32 v[56:57], v[134:135], v[8:9], v[56:57] op_sel_hi:[1,0,1]
	global_load_dwordx4 v[6:9], v[6:7], off
	v_pk_fma_f32 v[126:127], v[138:139], v[4:5], v[56:57] op_sel_hi:[1,0,1]
	v_mov_b32_e32 v4, v5
	v_pk_fma_f32 v[42:43], v[134:135], v[28:29], v[42:43] op_sel_hi:[1,0,1]
	v_pk_fma_f32 v[26:27], v[136:137], v[28:29], v[26:27] op_sel_hi:[1,0,1]
	v_pk_fma_f32 v[134:135], v[138:139], v[4:5], v[54:55] op_sel_hi:[1,0,1]
	v_pk_fma_f32 v[136:137], v[140:141], v[4:5], v[2:3] op_sel_hi:[1,0,1]
	v_mov_b32_e32 v10, v29
	ds_read_b128 v[2:5], v1 offset:32
	v_pk_fma_f32 v[138:139], v[138:139], v[10:11], v[42:43] op_sel_hi:[1,0,1]
	v_pk_fma_f32 v[140:141], v[140:141], v[10:11], v[26:27] op_sel_hi:[1,0,1]
	ds_read_b128 v[10:13], v1 offset:48
	ds_read_b128 v[14:17], v1 offset:4128
	ds_read_b128 v[18:21], v1 offset:8224
	ds_read_b128 v[22:25], v1 offset:4144
	s_waitcnt vmcnt(3) lgkmcnt(4)
	v_pk_fma_f32 v[144:145], v[32:33], v[2:3], v[50:51] op_sel_hi:[1,0,1]
	v_lshl_add_u64 v[50:51], v[124:125], 0, v[118:119]
	v_lshl_add_u64 v[54:55], v[124:125], 0, v[120:121]
	s_waitcnt lgkmcnt(1)
	v_pk_fma_f32 v[150:151], v[30:31], v[18:19], v[46:47] op_sel_hi:[1,0,1]
	v_lshl_add_u64 v[46:47], v[124:125], 0, v[116:117]
	v_pk_fma_f32 v[142:143], v[30:31], v[2:3], v[44:45] op_sel_hi:[1,0,1]
	ds_read_b128 v[26:29], v1 offset:8240
	ds_read_b128 v[42:45], v1 offset:12320
	global_load_dwordx4 v[46:49], v[46:47], off
	s_nop 0
	global_load_dwordx4 v[50:53], v[50:51], off
	s_nop 0
	global_load_dwordx4 v[54:57], v[54:55], off
	v_lshl_add_u64 v[66:67], v[124:125], 0, v[122:123]
	global_load_dwordx4 v[66:69], v[66:67], off
	v_pk_fma_f32 v[146:147], v[30:31], v[14:15], v[58:59] op_sel_hi:[1,0,1]
	v_pk_fma_f32 v[148:149], v[32:33], v[14:15], v[60:61] op_sel_hi:[1,0,1]
	v_pk_fma_f32 v[152:153], v[32:33], v[18:19], v[62:63] op_sel_hi:[1,0,1]
	ds_read_b128 v[58:61], v1 offset:12336
	s_waitcnt lgkmcnt(1)
	v_pk_fma_f32 v[154:155], v[30:31], v[42:43], v[64:65] op_sel_hi:[1,0,1]
	ds_read_b128 v[62:65], v1 offset:16416
	v_pk_fma_f32 v[156:157], v[32:33], v[42:43], v[70:71] op_sel_hi:[1,0,1]
	ds_read_b128 v[70:73], v1 offset:16432
	ds_read_b128 v[74:77], v1 offset:20512
	s_waitcnt lgkmcnt(2)
	v_pk_fma_f32 v[158:159], v[30:31], v[62:63], v[78:79] op_sel_hi:[1,0,1]
	v_pk_fma_f32 v[160:161], v[32:33], v[62:63], v[80:81] op_sel_hi:[1,0,1]
	ds_read_b128 v[78:81], v1 offset:20528
	ds_read_b128 v[82:85], v1 offset:24608
	s_waitcnt lgkmcnt(2)
	v_pk_fma_f32 v[162:163], v[30:31], v[74:75], v[126:127] op_sel_hi:[1,0,1]
	v_pk_fma_f32 v[164:165], v[32:33], v[74:75], v[130:131] op_sel_hi:[1,0,1]
	ds_read_b128 v[124:127], v1 offset:28704
	ds_read_b128 v[130:133], v1 offset:24624
	s_waitcnt lgkmcnt(2)
	v_pk_fma_f32 v[166:167], v[30:31], v[82:83], v[134:135] op_sel_hi:[1,0,1]
	v_pk_fma_f32 v[168:169], v[32:33], v[82:83], v[136:137] op_sel_hi:[1,0,1]
	s_waitcnt lgkmcnt(1)
	v_pk_fma_f32 v[30:31], v[30:31], v[124:125], v[138:139] op_sel_hi:[1,0,1]
	v_pk_fma_f32 v[32:33], v[32:33], v[124:125], v[140:141] op_sel_hi:[1,0,1]
	ds_read_b128 v[134:137], v1 offset:28720
	s_waitcnt vmcnt(6)
	v_pk_fma_f32 v[138:139], v[34:35], v[2:3], v[142:143] op_sel:[0,1,0]
	v_pk_fma_f32 v[2:3], v[36:37], v[2:3], v[144:145] op_sel:[0,1,0]
	v_pk_fma_f32 v[140:141], v[34:35], v[14:15], v[146:147] op_sel:[0,1,0]
	v_pk_fma_f32 v[14:15], v[36:37], v[14:15], v[148:149] op_sel:[0,1,0]
	v_pk_fma_f32 v[142:143], v[34:35], v[18:19], v[150:151] op_sel:[0,1,0]
	v_pk_fma_f32 v[144:145], v[34:35], v[42:43], v[154:155] op_sel:[0,1,0]
	v_pk_fma_f32 v[146:147], v[34:35], v[62:63], v[158:159] op_sel:[0,1,0]
	v_pk_fma_f32 v[148:149], v[34:35], v[74:75], v[162:163] op_sel:[0,1,0]
	v_pk_fma_f32 v[150:151], v[34:35], v[82:83], v[166:167] op_sel:[0,1,0]
	v_pk_fma_f32 v[30:31], v[34:35], v[124:125], v[30:31] op_sel:[0,1,0]
	s_waitcnt vmcnt(5)
; DEV void mod_phase(LAS char* shm, const float* c, const float* w_mod, const float* b_mod, float* mod, unsigned* modcnt) {
;     ...
;         for (int k = 0; k < 16; ++k) w[k] = *(const float4*)(W + (size_t)(kg * 16 + k) * 3 * DM);
; #pragma unroll
;         for (int k = 0; k < 16; ++k) {
; #pragma unroll
;             for (int b = 0; b < BATCH; ++b) { const float s_ = sc[b * DM + kg * 16 + k]; acc[b][0] += s_ * w[k].x; acc[b][1] += s_ * w[k].y; acc[b][2] += s_ * w[k].z; acc[b][3] += s_ * w[k].w; }
	v_pk_fma_f32 v[34:35], v[38:39], v[4:5], v[138:139] op_sel_hi:[1,0,1]
	v_pk_fma_f32 v[2:3], v[40:41], v[4:5], v[2:3] op_sel_hi:[1,0,1]
	v_mov_b32_e32 v4, v5
	v_pk_fma_f32 v[18:19], v[36:37], v[18:19], v[152:153] op_sel:[0,1,0]
	v_pk_fma_f32 v[42:43], v[36:37], v[42:43], v[156:157] op_sel:[0,1,0]
	v_pk_fma_f32 v[62:63], v[36:37], v[62:63], v[160:161] op_sel:[0,1,0]
	v_pk_fma_f32 v[74:75], v[36:37], v[74:75], v[164:165] op_sel:[0,1,0]
	v_pk_fma_f32 v[82:83], v[36:37], v[82:83], v[168:169] op_sel:[0,1,0]
	v_pk_fma_f32 v[32:33], v[36:37], v[124:125], v[32:33] op_sel:[0,1,0]
	v_pk_fma_f32 v[36:37], v[38:39], v[16:17], v[140:141] op_sel_hi:[1,0,1]
	v_pk_fma_f32 v[14:15], v[40:41], v[16:17], v[14:15] op_sel_hi:[1,0,1]
	s_waitcnt vmcnt(4)
	v_pk_fma_f32 v[34:35], v[6:7], v[4:5], v[34:35] op_sel_hi:[1,0,1]
	v_pk_fma_f32 v[2:3], v[8:9], v[4:5], v[2:3] op_sel_hi:[1,0,1]
	v_mov_b32_e32 v4, v17
	v_pk_fma_f32 v[124:125], v[38:39], v[20:21], v[142:143] op_sel_hi:[1,0,1]
	v_pk_fma_f32 v[18:19], v[40:41], v[20:21], v[18:19] op_sel_hi:[1,0,1]
	v_pk_fma_f32 v[16:17], v[6:7], v[4:5], v[36:37] op_sel_hi:[1,0,1]
	v_pk_fma_f32 v[14:15], v[8:9], v[4:5], v[14:15] op_sel_hi:[1,0,1]
	v_mov_b32_e32 v4, v21
	v_pk_fma_f32 v[138:139], v[38:39], v[44:45], v[144:145] op_sel_hi:[1,0,1]
	v_pk_fma_f32 v[42:43], v[40:41], v[44:45], v[42:43] op_sel_hi:[1,0,1]
	v_pk_fma_f32 v[20:21], v[6:7], v[4:5], v[124:125] op_sel_hi:[1,0,1]
	v_pk_fma_f32 v[18:19], v[8:9], v[4:5], v[18:19] op_sel_hi:[1,0,1]
	v_mov_b32_e32 v4, v45
	v_pk_fma_f32 v[140:141], v[38:39], v[64:65], v[146:147] op_sel_hi:[1,0,1]
	v_pk_fma_f32 v[62:63], v[40:41], v[64:65], v[62:63] op_sel_hi:[1,0,1]
	v_pk_fma_f32 v[142:143], v[38:39], v[76:77], v[148:149] op_sel_hi:[1,0,1]
	v_pk_fma_f32 v[144:145], v[38:39], v[84:85], v[150:151] op_sel_hi:[1,0,1]
	v_pk_fma_f32 v[30:31], v[38:39], v[126:127], v[30:31] op_sel_hi:[1,0,1]
	v_pk_fma_f32 v[36:37], v[6:7], v[4:5], v[138:139] op_sel_hi:[1,0,1]
	v_pk_fma_f32 v[38:39], v[8:9], v[4:5], v[42:43] op_sel_hi:[1,0,1]
	v_mov_b32_e32 v4, v65
	v_pk_fma_f32 v[74:75], v[40:41], v[76:77], v[74:75] op_sel_hi:[1,0,1]
	v_pk_fma_f32 v[82:83], v[40:41], v[84:85], v[82:83] op_sel_hi:[1,0,1]
	v_pk_fma_f32 v[32:33], v[40:41], v[126:127], v[32:33] op_sel_hi:[1,0,1]
	v_pk_fma_f32 v[40:41], v[6:7], v[4:5], v[140:141] op_sel_hi:[1,0,1]
	v_pk_fma_f32 v[42:43], v[8:9], v[4:5], v[62:63] op_sel_hi:[1,0,1]
	v_mov_b32_e32 v4, v77
	v_pk_fma_f32 v[44:45], v[6:7], v[4:5], v[142:143] op_sel_hi:[1,0,1]
	v_pk_fma_f32 v[62:63], v[8:9], v[4:5], v[74:75] op_sel_hi:[1,0,1]
	v_mov_b32_e32 v4, v85
	v_pk_fma_f32 v[64:65], v[6:7], v[4:5], v[144:145] op_sel_hi:[1,0,1]
	v_pk_fma_f32 v[74:75], v[8:9], v[4:5], v[82:83] op_sel_hi:[1,0,1]
	v_mov_b32_e32 v4, v127
	v_pk_fma_f32 v[30:31], v[6:7], v[4:5], v[30:31] op_sel_hi:[1,0,1]
	v_pk_fma_f32 v[32:33], v[8:9], v[4:5], v[32:33] op_sel_hi:[1,0,1]
	s_waitcnt vmcnt(3)
	v_pk_fma_f32 v[4:5], v[46:47], v[10:11], v[34:35] op_sel_hi:[1,0,1]
	v_pk_fma_f32 v[2:3], v[48:49], v[10:11], v[2:3] op_sel_hi:[1,0,1]
	s_waitcnt vmcnt(2)
	v_pk_fma_f32 v[4:5], v[50:51], v[10:11], v[4:5] op_sel:[0,1,0]
	v_pk_fma_f32 v[2:3], v[52:53], v[10:11], v[2:3] op_sel:[0,1,0]
	s_waitcnt vmcnt(1)
	v_pk_fma_f32 v[4:5], v[54:55], v[12:13], v[4:5] op_sel_hi:[1,0,1]
	v_pk_fma_f32 v[6:7], v[56:57], v[12:13], v[2:3] op_sel_hi:[1,0,1]
	v_mov_b32_e32 v8, v13
	s_waitcnt vmcnt(0)
; #define LAS __attribute__((address_space(3)))
; #define mod ((float*)S7(MOD_OFF))
; DEV void mod_phase(LAS char* shm, const float* c, const float* w_mod, const float* b_mod, float* mod, unsigned* modcnt) {
;     ...
;         for (int k = 0; k < 16; ++k) {
; #pragma unroll
;             for (int b = 0; b < BATCH; ++b) { const float s_ = sc[b * DM + kg * 16 + k]; acc[b][0] += s_ * w[k].x; acc[b][1] += s_ * w[k].y; acc[b][2] += s_ * w[k].z; acc[b][3] += s_ * w[k].w; }
;         }
; #pragma unroll
;         for (int b = 0; b < BATCH; ++b) *(LAS f32x4*)(pr + (kg * 8 + b) * 32 + 4 * cq) = (f32x4){acc[b][0], acc[b][1], acc[b][2], acc[b][3]};
;         __syncthreads();
;         if (tid < 256) {
;             const int b = tid >> 5, n = tid & 31; float s_ = 0.f;
; #pragma unroll 8
;             for (int g2 = 0; g2 < 64; ++g2) s_ += pr[(g2 * 8 + b) * 32 + n];
;             __hip_atomic_store(mod + ((size_t)l * BATCH + b) * 3 * DM + n0 + n, s_ + b_mod[l * 3 * DM + n0 + n], __ATOMIC_RELAXED, __HIP_MEMORY_SCOPE_AGENT);
	v_pk_fma_f32 v[2:3], v[66:67], v[8:9], v[4:5] op_sel_hi:[1,0,1]
	v_pk_fma_f32 v[4:5], v[68:69], v[8:9], v[6:7] op_sel_hi:[1,0,1]
	v_pk_fma_f32 v[6:7], v[46:47], v[22:23], v[16:17] op_sel_hi:[1,0,1]
	v_pk_fma_f32 v[8:9], v[48:49], v[22:23], v[14:15] op_sel_hi:[1,0,1]
	v_pk_fma_f32 v[6:7], v[50:51], v[22:23], v[6:7] op_sel:[0,1,0]
	v_pk_fma_f32 v[8:9], v[52:53], v[22:23], v[8:9] op_sel:[0,1,0]
	v_pk_fma_f32 v[6:7], v[54:55], v[24:25], v[6:7] op_sel_hi:[1,0,1]
	v_pk_fma_f32 v[8:9], v[56:57], v[24:25], v[8:9] op_sel_hi:[1,0,1]
	v_mov_b32_e32 v10, v25
	v_pk_fma_f32 v[6:7], v[66:67], v[10:11], v[6:7] op_sel_hi:[1,0,1]
	v_pk_fma_f32 v[8:9], v[68:69], v[10:11], v[8:9] op_sel_hi:[1,0,1]
	v_pk_fma_f32 v[10:11], v[46:47], v[26:27], v[20:21] op_sel_hi:[1,0,1]
	v_pk_fma_f32 v[12:13], v[48:49], v[26:27], v[18:19] op_sel_hi:[1,0,1]
	v_pk_fma_f32 v[10:11], v[50:51], v[26:27], v[10:11] op_sel:[0,1,0]
	v_pk_fma_f32 v[12:13], v[52:53], v[26:27], v[12:13] op_sel:[0,1,0]
	v_pk_fma_f32 v[10:11], v[54:55], v[28:29], v[10:11] op_sel_hi:[1,0,1]
	v_pk_fma_f32 v[12:13], v[56:57], v[28:29], v[12:13] op_sel_hi:[1,0,1]
	v_mov_b32_e32 v14, v29
	v_pk_fma_f32 v[10:11], v[66:67], v[14:15], v[10:11] op_sel_hi:[1,0,1]
	v_pk_fma_f32 v[12:13], v[68:69], v[14:15], v[12:13] op_sel_hi:[1,0,1]
	v_pk_fma_f32 v[14:15], v[46:47], v[58:59], v[36:37] op_sel_hi:[1,0,1]
	v_pk_fma_f32 v[16:17], v[48:49], v[58:59], v[38:39] op_sel_hi:[1,0,1]
	v_pk_fma_f32 v[14:15], v[50:51], v[58:59], v[14:15] op_sel:[0,1,0]
	v_pk_fma_f32 v[16:17], v[52:53], v[58:59], v[16:17] op_sel:[0,1,0]
	v_pk_fma_f32 v[14:15], v[54:55], v[60:61], v[14:15] op_sel_hi:[1,0,1]
	v_pk_fma_f32 v[16:17], v[56:57], v[60:61], v[16:17] op_sel_hi:[1,0,1]
	v_mov_b32_e32 v18, v61
	v_pk_fma_f32 v[14:15], v[66:67], v[18:19], v[14:15] op_sel_hi:[1,0,1]
	v_pk_fma_f32 v[16:17], v[68:69], v[18:19], v[16:17] op_sel_hi:[1,0,1]
	v_pk_fma_f32 v[18:19], v[46:47], v[70:71], v[40:41] op_sel_hi:[1,0,1]
	v_pk_fma_f32 v[20:21], v[48:49], v[70:71], v[42:43] op_sel_hi:[1,0,1]
	v_pk_fma_f32 v[18:19], v[50:51], v[70:71], v[18:19] op_sel:[0,1,0]
	v_pk_fma_f32 v[20:21], v[52:53], v[70:71], v[20:21] op_sel:[0,1,0]
	v_pk_fma_f32 v[18:19], v[54:55], v[72:73], v[18:19] op_sel_hi:[1,0,1]
	v_pk_fma_f32 v[20:21], v[56:57], v[72:73], v[20:21] op_sel_hi:[1,0,1]
	v_mov_b32_e32 v22, v73
	v_pk_fma_f32 v[18:19], v[66:67], v[22:23], v[18:19] op_sel_hi:[1,0,1]
	v_pk_fma_f32 v[20:21], v[68:69], v[22:23], v[20:21] op_sel_hi:[1,0,1]
	v_pk_fma_f32 v[22:23], v[46:47], v[78:79], v[44:45] op_sel_hi:[1,0,1]
	v_pk_fma_f32 v[24:25], v[48:49], v[78:79], v[62:63] op_sel_hi:[1,0,1]
	v_pk_fma_f32 v[22:23], v[50:51], v[78:79], v[22:23] op_sel:[0,1,0]
	v_pk_fma_f32 v[24:25], v[52:53], v[78:79], v[24:25] op_sel:[0,1,0]
	v_pk_fma_f32 v[22:23], v[54:55], v[80:81], v[22:23] op_sel_hi:[1,0,1]
	v_pk_fma_f32 v[24:25], v[56:57], v[80:81], v[24:25] op_sel_hi:[1,0,1]
	v_mov_b32_e32 v26, v81
	v_pk_fma_f32 v[22:23], v[66:67], v[26:27], v[22:23] op_sel_hi:[1,0,1]
	v_pk_fma_f32 v[24:25], v[68:69], v[26:27], v[24:25] op_sel_hi:[1,0,1]
	s_waitcnt lgkmcnt(1)
	v_pk_fma_f32 v[26:27], v[46:47], v[130:131], v[64:65] op_sel_hi:[1,0,1]
	v_pk_fma_f32 v[28:29], v[48:49], v[130:131], v[74:75] op_sel_hi:[1,0,1]
	v_pk_fma_f32 v[26:27], v[50:51], v[130:131], v[26:27] op_sel:[0,1,0]
	v_pk_fma_f32 v[28:29], v[52:53], v[130:131], v[28:29] op_sel:[0,1,0]
	s_waitcnt lgkmcnt(0)
	v_pk_fma_f32 v[30:31], v[46:47], v[134:135], v[30:31] op_sel_hi:[1,0,1]
	v_pk_fma_f32 v[32:33], v[48:49], v[134:135], v[32:33] op_sel_hi:[1,0,1]
	v_pk_fma_f32 v[26:27], v[54:55], v[132:133], v[26:27] op_sel_hi:[1,0,1]
	v_pk_fma_f32 v[28:29], v[56:57], v[132:133], v[28:29] op_sel_hi:[1,0,1]
	v_mov_b32_e32 v34, v133
	v_pk_fma_f32 v[30:31], v[50:51], v[134:135], v[30:31] op_sel:[0,1,0]
	v_pk_fma_f32 v[32:33], v[52:53], v[134:135], v[32:33] op_sel:[0,1,0]
	v_pk_fma_f32 v[26:27], v[66:67], v[34:35], v[26:27] op_sel_hi:[1,0,1]
	v_pk_fma_f32 v[28:29], v[68:69], v[34:35], v[28:29] op_sel_hi:[1,0,1]
	v_pk_fma_f32 v[30:31], v[54:55], v[136:137], v[30:31] op_sel_hi:[1,0,1]
	v_pk_fma_f32 v[32:33], v[56:57], v[136:137], v[32:33] op_sel_hi:[1,0,1]
	v_mov_b32_e32 v34, v137
	v_pk_fma_f32 v[30:31], v[66:67], v[34:35], v[30:31] op_sel_hi:[1,0,1]
	v_pk_fma_f32 v[32:33], v[68:69], v[34:35], v[32:33] op_sel_hi:[1,0,1]
	ds_write_b128 v128, v[2:5] offset:32768
	ds_write_b128 v128, v[6:9] offset:32896
	ds_write_b128 v128, v[10:13] offset:33024
	ds_write_b128 v128, v[14:17] offset:33152
	ds_write_b128 v128, v[18:21] offset:33280
	ds_write_b128 v128, v[22:25] offset:33408
	ds_write_b128 v128, v[26:29] offset:33536
	ds_write_b128 v129, v[30:33] offset:32768
	s_waitcnt lgkmcnt(0)
	s_barrier
	s_and_saveexec_b64 s[16:17], vcc
	s_cbranch_execz .LBB0_15
	s_ashr_i32 s15, s14, 31
	v_mov_b32_e32 v2, 0
	s_mul_i32 s20, s14, 0xc00
	s_add_i32 s20, s20, s6
	v_or_b32_e32 v12, s20, v90
	v_ashrrev_i32_e32 v13, 31, v12
	v_lshl_add_u64 v[12:13], v[12:13], 2, s[8:9]
	global_load_dword v14, v[12:13], off
	s_mov_b32 s20, 0
.LBB0_13:
	v_add_u32_e32 v0, s20, v91
	ds_read2st64_b32 v[4:5], v0 offset1:4
	ds_read2st64_b32 v[6:7], v0 offset0:8 offset1:12
	ds_read2st64_b32 v[8:9], v0 offset0:16 offset1:20
	ds_read2st64_b32 v[10:11], v0 offset0:24 offset1:28
	s_addk_i32 s20, 0x2000
	s_waitcnt lgkmcnt(3)
	v_add_f32_e32 v0, v2, v4
	v_add_f32_e32 v0, v0, v5
	s_waitcnt lgkmcnt(2)
	v_add_f32_e32 v0, v0, v6
	v_add_f32_e32 v0, v0, v7
	s_waitcnt lgkmcnt(1)
	v_add_f32_e32 v0, v0, v8
	v_add_f32_e32 v0, v0, v9
	s_waitcnt lgkmcnt(0)
	v_add_f32_e32 v0, v0, v10
	s_cmp_eq_u32 s20, 0x10000
	v_add_f32_e32 v2, v0, v11
	s_cbranch_scc0 .LBB0_13
	v_lshl_add_u64 v[4:5], s[14:15], 3, v[88:89]
	v_mov_b64_e32 v[6:7], s[10:11]
	v_mad_u64_u32 v[6:7], s[14:15], v4, s18, v[6:7]
	v_mad_i32_i24 v7, v5, s18, v7
	v_lshl_add_u64 v[4:5], s[6:7], 2, v[6:7]
	v_lshlrev_b32_e32 v6, 2, v90
	v_mov_b32_e32 v7, v87
	v_lshl_add_u64 v[4:5], v[4:5], 0, v[6:7]
	s_waitcnt vmcnt(0)
	v_add_f32_e32 v0, v2, v14
	global_store_dword v[4:5], v0, off sc1
